# ResNorm epilogue part2 hand-written: bf16 H stored as 16B via v_permlane16_swap (half the store instructions), straight-line
# speedup vs baseline: 1.0946x; 1.0117x over previous
.LBB0_938:
	v_lshl_add_u32 v178, v160, 2, 0
	v_cndmask_b32_e64 v161, 0, 1, s[20:21]
	v_bfe_u32 v250, v224, 4, 1
	v_mov_b32_e32 v251, 0
	v_cmp_ne_u32_e64 s[38:39], 1, v161
	v_mul_u32_u24_e32 v250, 24, v250
	s_lshl_b64 s[0:1], s[22:23], 19
	v_readlane_b32 s2, v254, 53
	v_readlane_b32 s3, v254, 54
	s_add_u32 s2, s2, s0
	s_addc_u32 s3, s3, s1
	s_waitcnt vmcnt(0)
	ds_read_b32 v242, v178 offset:8192
	ds_read_b32 v244, v178 offset:8256
	ds_read_b32 v246, v178 offset:8320
	ds_read_b32 v184, v178 offset:8384
	ds_read_b32 v212, v178 offset:8704
	ds_read_b32 v210, v178 offset:8768
	ds_read_b32 v160, v178 offset:8832
	ds_read_b32 v224, v178 offset:8896
	s_waitcnt lgkmcnt(7)
	v_pk_mul_f32 v[226:227], v[156:157], v[242:243] op_sel_hi:[1,0]
	v_pk_mul_f32 v[228:229], v[158:159], v[242:243] op_sel_hi:[1,0]
	v_pk_mul_f32 v[230:231], v[152:153], v[242:243] op_sel_hi:[1,0]
	v_pk_mul_f32 v[232:233], v[154:155], v[242:243] op_sel_hi:[1,0]
	v_pk_mul_f32 v[234:235], v[148:149], v[242:243] op_sel_hi:[1,0]
	v_pk_mul_f32 v[236:237], v[150:151], v[242:243] op_sel_hi:[1,0]
	v_pk_mul_f32 v[238:239], v[116:117], v[242:243] op_sel_hi:[1,0]
	v_pk_mul_f32 v[240:241], v[118:119], v[242:243] op_sel_hi:[1,0]
	v_pk_fma_f32 v[226:227], v[128:129], v[226:227], v[140:141]
	v_pk_fma_f32 v[228:229], v[130:131], v[228:229], v[142:143]
	v_pk_fma_f32 v[230:231], v[136:137], v[230:231], v[108:109]
	v_pk_fma_f32 v[232:233], v[138:139], v[232:233], v[110:111]
	v_pk_fma_f32 v[234:235], v[120:121], v[234:235], v[132:133]
	v_pk_fma_f32 v[236:237], v[122:123], v[236:237], v[134:135]
	v_pk_fma_f32 v[238:239], v[112:113], v[238:239], v[100:101]
	v_pk_fma_f32 v[240:241], v[114:115], v[240:241], v[102:103]
	s_and_b64 vcc, exec, s[38:39]
	s_cbranch_vccz .Lrn2_fin_0
	v_lshl_add_u64 v[248:249], v[206:207], 1, s[2:3]
	v_cvt_pk_bf16_f32 v226, v226, v227
	v_cvt_pk_bf16_f32 v227, v228, v229
	v_cvt_pk_bf16_f32 v228, v230, v231
	v_cvt_pk_bf16_f32 v229, v232, v233
	v_lshl_add_u64 v[248:249], v[248:249], 0, v[250:251]
	s_nop 0
	v_permlane16_swap_b32 v226, v228
	v_permlane16_swap_b32 v227, v229
	global_store_dwordx4 v[248:249], v[226:229], off
	v_cvt_pk_bf16_f32 v234, v234, v235
	v_cvt_pk_bf16_f32 v235, v236, v237
	v_cvt_pk_bf16_f32 v236, v238, v239
	v_cvt_pk_bf16_f32 v237, v240, v241
	s_nop 1
	v_permlane16_swap_b32 v234, v236
	v_permlane16_swap_b32 v235, v237
	global_store_dwordx4 v[248:249], v[234:237], off offset:256
	s_branch .Lrn2_nx_0
.Lrn2_fin_0:
	global_store_dwordx4 v[208:209], v[226:229], off nt
	global_store_dwordx4 v[208:209], v[230:233], off offset:64 nt
	global_store_dwordx4 v[208:209], v[234:237], off offset:512 nt
	global_store_dwordx4 v[208:209], v[238:241], off offset:576 nt
.Lrn2_nx_0:
	s_waitcnt lgkmcnt(6)
	v_pk_mul_f32 v[156:157], v[144:145], v[244:245] op_sel_hi:[1,0]
	v_pk_mul_f32 v[158:159], v[146:147], v[244:245] op_sel_hi:[1,0]
	v_pk_mul_f32 v[152:153], v[124:125], v[244:245] op_sel_hi:[1,0]
	v_pk_mul_f32 v[154:155], v[126:127], v[244:245] op_sel_hi:[1,0]
	v_pk_mul_f32 v[148:149], v[104:105], v[244:245] op_sel_hi:[1,0]
	v_pk_mul_f32 v[150:151], v[106:107], v[244:245] op_sel_hi:[1,0]
	v_pk_mul_f32 v[116:117], v[92:93], v[244:245] op_sel_hi:[1,0]
	v_pk_mul_f32 v[118:119], v[94:95], v[244:245] op_sel_hi:[1,0]
	v_pk_fma_f32 v[156:157], v[128:129], v[156:157], v[140:141]
	v_pk_fma_f32 v[158:159], v[130:131], v[158:159], v[142:143]
	v_pk_fma_f32 v[152:153], v[136:137], v[152:153], v[108:109]
	v_pk_fma_f32 v[154:155], v[138:139], v[154:155], v[110:111]
	v_pk_fma_f32 v[148:149], v[120:121], v[148:149], v[132:133]
	v_pk_fma_f32 v[150:151], v[122:123], v[150:151], v[134:135]
	v_pk_fma_f32 v[116:117], v[112:113], v[116:117], v[100:101]
	v_pk_fma_f32 v[118:119], v[114:115], v[118:119], v[102:103]
	s_and_b64 vcc, exec, s[38:39]
	s_cbranch_vccz .Lrn2_fin_1
	v_lshl_add_u64 v[248:249], v[202:203], 1, s[2:3]
	v_cvt_pk_bf16_f32 v156, v156, v157
	v_cvt_pk_bf16_f32 v157, v158, v159
	v_cvt_pk_bf16_f32 v158, v152, v153
	v_cvt_pk_bf16_f32 v159, v154, v155
	v_lshl_add_u64 v[248:249], v[248:249], 0, v[250:251]
	s_nop 0
	v_permlane16_swap_b32 v156, v158
	v_permlane16_swap_b32 v157, v159
	global_store_dwordx4 v[248:249], v[156:159], off
	v_cvt_pk_bf16_f32 v148, v148, v149
	v_cvt_pk_bf16_f32 v149, v150, v151
	v_cvt_pk_bf16_f32 v150, v116, v117
	v_cvt_pk_bf16_f32 v151, v118, v119
	s_nop 1
	v_permlane16_swap_b32 v148, v150
	v_permlane16_swap_b32 v149, v151
	global_store_dwordx4 v[248:249], v[148:151], off offset:256
	s_branch .Lrn2_nx_1
.Lrn2_fin_1:
	global_store_dwordx4 v[204:205], v[156:159], off nt
	global_store_dwordx4 v[204:205], v[152:155], off offset:64 nt
	global_store_dwordx4 v[204:205], v[148:151], off offset:512 nt
	global_store_dwordx4 v[204:205], v[116:119], off offset:576 nt
.Lrn2_nx_1:
	s_waitcnt lgkmcnt(5)
	v_pk_mul_f32 v[226:227], v[96:97], v[246:247] op_sel_hi:[1,0]
	v_pk_mul_f32 v[228:229], v[98:99], v[246:247] op_sel_hi:[1,0]
	v_pk_mul_f32 v[230:231], v[88:89], v[246:247] op_sel_hi:[1,0]
	v_pk_mul_f32 v[232:233], v[90:91], v[246:247] op_sel_hi:[1,0]
	v_pk_mul_f32 v[234:235], v[84:85], v[246:247] op_sel_hi:[1,0]
	v_pk_mul_f32 v[236:237], v[86:87], v[246:247] op_sel_hi:[1,0]
	v_pk_mul_f32 v[238:239], v[76:77], v[246:247] op_sel_hi:[1,0]
	v_pk_mul_f32 v[240:241], v[78:79], v[246:247] op_sel_hi:[1,0]
	v_pk_fma_f32 v[226:227], v[128:129], v[226:227], v[140:141]
	v_pk_fma_f32 v[228:229], v[130:131], v[228:229], v[142:143]
	v_pk_fma_f32 v[230:231], v[136:137], v[230:231], v[108:109]
	v_pk_fma_f32 v[232:233], v[138:139], v[232:233], v[110:111]
	v_pk_fma_f32 v[234:235], v[120:121], v[234:235], v[132:133]
	v_pk_fma_f32 v[236:237], v[122:123], v[236:237], v[134:135]
	v_pk_fma_f32 v[238:239], v[112:113], v[238:239], v[100:101]
	v_pk_fma_f32 v[240:241], v[114:115], v[240:241], v[102:103]
	s_and_b64 vcc, exec, s[38:39]
	s_cbranch_vccz .Lrn2_fin_2
	v_lshl_add_u64 v[248:249], v[198:199], 1, s[2:3]
	v_cvt_pk_bf16_f32 v226, v226, v227
	v_cvt_pk_bf16_f32 v227, v228, v229
	v_cvt_pk_bf16_f32 v228, v230, v231
	v_cvt_pk_bf16_f32 v229, v232, v233
	v_lshl_add_u64 v[248:249], v[248:249], 0, v[250:251]
	s_nop 0
	v_permlane16_swap_b32 v226, v228
	v_permlane16_swap_b32 v227, v229
	global_store_dwordx4 v[248:249], v[226:229], off
	v_cvt_pk_bf16_f32 v234, v234, v235
	v_cvt_pk_bf16_f32 v235, v236, v237
	v_cvt_pk_bf16_f32 v236, v238, v239
	v_cvt_pk_bf16_f32 v237, v240, v241
	s_nop 1
	v_permlane16_swap_b32 v234, v236
	v_permlane16_swap_b32 v235, v237
	global_store_dwordx4 v[248:249], v[234:237], off offset:256
	s_branch .Lrn2_nx_2
.Lrn2_fin_2:
	global_store_dwordx4 v[200:201], v[226:229], off nt
	global_store_dwordx4 v[200:201], v[230:233], off offset:64 nt
	global_store_dwordx4 v[200:201], v[234:237], off offset:512 nt
	global_store_dwordx4 v[200:201], v[238:241], off offset:576 nt
.Lrn2_nx_2:
	s_waitcnt lgkmcnt(4)
	v_pk_mul_f32 v[156:157], v[80:81], v[184:185] op_sel_hi:[1,0]
	v_pk_mul_f32 v[158:159], v[82:83], v[184:185] op_sel_hi:[1,0]
	v_pk_mul_f32 v[152:153], v[72:73], v[184:185] op_sel_hi:[1,0]
	v_pk_mul_f32 v[154:155], v[74:75], v[184:185] op_sel_hi:[1,0]
	v_pk_mul_f32 v[148:149], v[68:69], v[184:185] op_sel_hi:[1,0]
	v_pk_mul_f32 v[150:151], v[70:71], v[184:185] op_sel_hi:[1,0]
	v_pk_mul_f32 v[116:117], v[60:61], v[184:185] op_sel_hi:[1,0]
	v_pk_mul_f32 v[118:119], v[62:63], v[184:185] op_sel_hi:[1,0]
	v_pk_fma_f32 v[156:157], v[128:129], v[156:157], v[140:141]
	v_pk_fma_f32 v[158:159], v[130:131], v[158:159], v[142:143]
	v_pk_fma_f32 v[152:153], v[136:137], v[152:153], v[108:109]
	v_pk_fma_f32 v[154:155], v[138:139], v[154:155], v[110:111]
	v_pk_fma_f32 v[148:149], v[120:121], v[148:149], v[132:133]
	v_pk_fma_f32 v[150:151], v[122:123], v[150:151], v[134:135]
	v_pk_fma_f32 v[116:117], v[112:113], v[116:117], v[100:101]
	v_pk_fma_f32 v[118:119], v[114:115], v[118:119], v[102:103]
	s_and_b64 vcc, exec, s[38:39]
	s_cbranch_vccz .Lrn2_fin_3
	v_lshl_add_u64 v[248:249], v[194:195], 1, s[2:3]
	v_cvt_pk_bf16_f32 v156, v156, v157
	v_cvt_pk_bf16_f32 v157, v158, v159
	v_cvt_pk_bf16_f32 v158, v152, v153
	v_cvt_pk_bf16_f32 v159, v154, v155
	v_lshl_add_u64 v[248:249], v[248:249], 0, v[250:251]
	s_nop 0
	v_permlane16_swap_b32 v156, v158
	v_permlane16_swap_b32 v157, v159
	global_store_dwordx4 v[248:249], v[156:159], off
	v_cvt_pk_bf16_f32 v148, v148, v149
	v_cvt_pk_bf16_f32 v149, v150, v151
	v_cvt_pk_bf16_f32 v150, v116, v117
	v_cvt_pk_bf16_f32 v151, v118, v119
	s_nop 1
	v_permlane16_swap_b32 v148, v150
	v_permlane16_swap_b32 v149, v151
	global_store_dwordx4 v[248:249], v[148:151], off offset:256
	s_branch .Lrn2_nx_3
.Lrn2_fin_3:
	global_store_dwordx4 v[196:197], v[156:159], off nt
	global_store_dwordx4 v[196:197], v[152:155], off offset:64 nt
	global_store_dwordx4 v[196:197], v[148:151], off offset:512 nt
	global_store_dwordx4 v[196:197], v[116:119], off offset:576 nt
.Lrn2_nx_3:
	s_waitcnt lgkmcnt(3)
	v_pk_mul_f32 v[226:227], v[64:65], v[212:213] op_sel_hi:[1,0]
	v_pk_mul_f32 v[228:229], v[66:67], v[212:213] op_sel_hi:[1,0]
	v_pk_mul_f32 v[230:231], v[56:57], v[212:213] op_sel_hi:[1,0]
	v_pk_mul_f32 v[232:233], v[58:59], v[212:213] op_sel_hi:[1,0]
	v_pk_mul_f32 v[234:235], v[52:53], v[212:213] op_sel_hi:[1,0]
	v_pk_mul_f32 v[236:237], v[54:55], v[212:213] op_sel_hi:[1,0]
	v_pk_mul_f32 v[238:239], v[44:45], v[212:213] op_sel_hi:[1,0]
	v_pk_mul_f32 v[240:241], v[46:47], v[212:213] op_sel_hi:[1,0]
	v_pk_fma_f32 v[226:227], v[128:129], v[226:227], v[140:141]
	v_pk_fma_f32 v[228:229], v[130:131], v[228:229], v[142:143]
	v_pk_fma_f32 v[230:231], v[136:137], v[230:231], v[108:109]
	v_pk_fma_f32 v[232:233], v[138:139], v[232:233], v[110:111]
	v_pk_fma_f32 v[234:235], v[120:121], v[234:235], v[132:133]
	v_pk_fma_f32 v[236:237], v[122:123], v[236:237], v[134:135]
	v_pk_fma_f32 v[238:239], v[112:113], v[238:239], v[100:101]
	v_pk_fma_f32 v[240:241], v[114:115], v[240:241], v[102:103]
	s_and_b64 vcc, exec, s[38:39]
	s_cbranch_vccz .Lrn2_fin_4
	v_lshl_add_u64 v[248:249], v[174:175], 1, s[2:3]
	v_cvt_pk_bf16_f32 v226, v226, v227
	v_cvt_pk_bf16_f32 v227, v228, v229
	v_cvt_pk_bf16_f32 v228, v230, v231
	v_cvt_pk_bf16_f32 v229, v232, v233
	v_lshl_add_u64 v[248:249], v[248:249], 0, v[250:251]
	s_nop 0
	v_permlane16_swap_b32 v226, v228
	v_permlane16_swap_b32 v227, v229
	global_store_dwordx4 v[248:249], v[226:229], off
	v_cvt_pk_bf16_f32 v234, v234, v235
	v_cvt_pk_bf16_f32 v235, v236, v237
	v_cvt_pk_bf16_f32 v236, v238, v239
	v_cvt_pk_bf16_f32 v237, v240, v241
	s_nop 1
	v_permlane16_swap_b32 v234, v236
	v_permlane16_swap_b32 v235, v237
	global_store_dwordx4 v[248:249], v[234:237], off offset:256
	s_branch .Lrn2_nx_4
.Lrn2_fin_4:
	global_store_dwordx4 v[176:177], v[226:229], off nt
	global_store_dwordx4 v[176:177], v[230:233], off offset:64 nt
	global_store_dwordx4 v[176:177], v[234:237], off offset:512 nt
	global_store_dwordx4 v[176:177], v[238:241], off offset:576 nt
.Lrn2_nx_4:
	s_waitcnt lgkmcnt(2)
	v_pk_mul_f32 v[156:157], v[48:49], v[210:211] op_sel_hi:[1,0]
	v_pk_mul_f32 v[158:159], v[50:51], v[210:211] op_sel_hi:[1,0]
	v_pk_mul_f32 v[152:153], v[40:41], v[210:211] op_sel_hi:[1,0]
	v_pk_mul_f32 v[154:155], v[42:43], v[210:211] op_sel_hi:[1,0]
	v_pk_mul_f32 v[148:149], v[36:37], v[210:211] op_sel_hi:[1,0]
	v_pk_mul_f32 v[150:151], v[38:39], v[210:211] op_sel_hi:[1,0]
	v_pk_mul_f32 v[116:117], v[32:33], v[210:211] op_sel_hi:[1,0]
	v_pk_mul_f32 v[118:119], v[34:35], v[210:211] op_sel_hi:[1,0]
	v_pk_fma_f32 v[156:157], v[128:129], v[156:157], v[140:141]
	v_pk_fma_f32 v[158:159], v[130:131], v[158:159], v[142:143]
	v_pk_fma_f32 v[152:153], v[136:137], v[152:153], v[108:109]
	v_pk_fma_f32 v[154:155], v[138:139], v[154:155], v[110:111]
	v_pk_fma_f32 v[148:149], v[120:121], v[148:149], v[132:133]
	v_pk_fma_f32 v[150:151], v[122:123], v[150:151], v[134:135]
	v_pk_fma_f32 v[116:117], v[112:113], v[116:117], v[100:101]
	v_pk_fma_f32 v[118:119], v[114:115], v[118:119], v[102:103]
	s_and_b64 vcc, exec, s[38:39]
	s_cbranch_vccz .Lrn2_fin_5
	v_lshl_add_u64 v[248:249], v[170:171], 1, s[2:3]
	v_cvt_pk_bf16_f32 v156, v156, v157
	v_cvt_pk_bf16_f32 v157, v158, v159
	v_cvt_pk_bf16_f32 v158, v152, v153
	v_cvt_pk_bf16_f32 v159, v154, v155
	v_lshl_add_u64 v[248:249], v[248:249], 0, v[250:251]
	s_nop 0
	v_permlane16_swap_b32 v156, v158
	v_permlane16_swap_b32 v157, v159
	global_store_dwordx4 v[248:249], v[156:159], off
	v_cvt_pk_bf16_f32 v148, v148, v149
	v_cvt_pk_bf16_f32 v149, v150, v151
	v_cvt_pk_bf16_f32 v150, v116, v117
	v_cvt_pk_bf16_f32 v151, v118, v119
	s_nop 1
	v_permlane16_swap_b32 v148, v150
	v_permlane16_swap_b32 v149, v151
	global_store_dwordx4 v[248:249], v[148:151], off offset:256
	s_branch .Lrn2_nx_5
.Lrn2_fin_5:
	global_store_dwordx4 v[172:173], v[156:159], off nt
	global_store_dwordx4 v[172:173], v[152:155], off offset:64 nt
	global_store_dwordx4 v[172:173], v[148:151], off offset:512 nt
	global_store_dwordx4 v[172:173], v[116:119], off offset:576 nt
.Lrn2_nx_5:
	s_waitcnt lgkmcnt(1)
	v_pk_mul_f32 v[226:227], v[28:29], v[160:161] op_sel_hi:[1,0]
	v_pk_mul_f32 v[228:229], v[30:31], v[160:161] op_sel_hi:[1,0]
	v_pk_mul_f32 v[230:231], v[24:25], v[160:161] op_sel_hi:[1,0]
	v_pk_mul_f32 v[232:233], v[26:27], v[160:161] op_sel_hi:[1,0]
	v_pk_mul_f32 v[234:235], v[20:21], v[160:161] op_sel_hi:[1,0]
	v_pk_mul_f32 v[236:237], v[22:23], v[160:161] op_sel_hi:[1,0]
	v_pk_mul_f32 v[238:239], v[16:17], v[160:161] op_sel_hi:[1,0]
	v_pk_mul_f32 v[240:241], v[18:19], v[160:161] op_sel_hi:[1,0]
	v_pk_fma_f32 v[226:227], v[128:129], v[226:227], v[140:141]
	v_pk_fma_f32 v[228:229], v[130:131], v[228:229], v[142:143]
	v_pk_fma_f32 v[230:231], v[136:137], v[230:231], v[108:109]
	v_pk_fma_f32 v[232:233], v[138:139], v[232:233], v[110:111]
	v_pk_fma_f32 v[234:235], v[120:121], v[234:235], v[132:133]
	v_pk_fma_f32 v[236:237], v[122:123], v[236:237], v[134:135]
	v_pk_fma_f32 v[238:239], v[112:113], v[238:239], v[100:101]
	v_pk_fma_f32 v[240:241], v[114:115], v[240:241], v[102:103]
	s_and_b64 vcc, exec, s[38:39]
	s_cbranch_vccz .Lrn2_fin_6
	v_lshl_add_u64 v[248:249], v[166:167], 1, s[2:3]
	v_cvt_pk_bf16_f32 v226, v226, v227
	v_cvt_pk_bf16_f32 v227, v228, v229
	v_cvt_pk_bf16_f32 v228, v230, v231
	v_cvt_pk_bf16_f32 v229, v232, v233
	v_lshl_add_u64 v[248:249], v[248:249], 0, v[250:251]
	s_nop 0
	v_permlane16_swap_b32 v226, v228
	v_permlane16_swap_b32 v227, v229
	global_store_dwordx4 v[248:249], v[226:229], off
	v_cvt_pk_bf16_f32 v234, v234, v235
	v_cvt_pk_bf16_f32 v235, v236, v237
	v_cvt_pk_bf16_f32 v236, v238, v239
	v_cvt_pk_bf16_f32 v237, v240, v241
	s_nop 1
	v_permlane16_swap_b32 v234, v236
	v_permlane16_swap_b32 v235, v237
	global_store_dwordx4 v[248:249], v[234:237], off offset:256
	s_branch .Lrn2_nx_6
.Lrn2_fin_6:
	global_store_dwordx4 v[168:169], v[226:229], off nt
	global_store_dwordx4 v[168:169], v[230:233], off offset:64 nt
	global_store_dwordx4 v[168:169], v[234:237], off offset:512 nt
	global_store_dwordx4 v[168:169], v[238:241], off offset:576 nt
.Lrn2_nx_6:
	s_waitcnt lgkmcnt(0)
	v_pk_mul_f32 v[156:157], v[12:13], v[224:225] op_sel_hi:[1,0]
	v_pk_mul_f32 v[158:159], v[14:15], v[224:225] op_sel_hi:[1,0]
	v_pk_mul_f32 v[152:153], v[8:9], v[224:225] op_sel_hi:[1,0]
	v_pk_mul_f32 v[154:155], v[10:11], v[224:225] op_sel_hi:[1,0]
	v_pk_mul_f32 v[148:149], v[4:5], v[224:225] op_sel_hi:[1,0]
	v_pk_mul_f32 v[150:151], v[6:7], v[224:225] op_sel_hi:[1,0]
	v_pk_mul_f32 v[116:117], v[0:1], v[224:225] op_sel_hi:[1,0]
	v_pk_mul_f32 v[118:119], v[2:3], v[224:225] op_sel_hi:[1,0]
	v_pk_fma_f32 v[156:157], v[128:129], v[156:157], v[140:141]
	v_pk_fma_f32 v[158:159], v[130:131], v[158:159], v[142:143]
	v_pk_fma_f32 v[152:153], v[136:137], v[152:153], v[108:109]
	v_pk_fma_f32 v[154:155], v[138:139], v[154:155], v[110:111]
	v_pk_fma_f32 v[148:149], v[120:121], v[148:149], v[132:133]
	v_pk_fma_f32 v[150:151], v[122:123], v[150:151], v[134:135]
	v_pk_fma_f32 v[116:117], v[112:113], v[116:117], v[100:101]
	v_pk_fma_f32 v[118:119], v[114:115], v[118:119], v[102:103]
	s_and_b64 vcc, exec, s[38:39]
	s_cbranch_vccz .Lrn2_fin_7
	v_lshl_add_u64 v[248:249], v[162:163], 1, s[2:3]
	v_cvt_pk_bf16_f32 v156, v156, v157
	v_cvt_pk_bf16_f32 v157, v158, v159
	v_cvt_pk_bf16_f32 v158, v152, v153
	v_cvt_pk_bf16_f32 v159, v154, v155
	v_lshl_add_u64 v[248:249], v[248:249], 0, v[250:251]
	s_nop 0
	v_permlane16_swap_b32 v156, v158
	v_permlane16_swap_b32 v157, v159
	global_store_dwordx4 v[248:249], v[156:159], off
	v_cvt_pk_bf16_f32 v148, v148, v149
	v_cvt_pk_bf16_f32 v149, v150, v151
	v_cvt_pk_bf16_f32 v150, v116, v117
	v_cvt_pk_bf16_f32 v151, v118, v119
	s_nop 1
	v_permlane16_swap_b32 v148, v150
	v_permlane16_swap_b32 v149, v151
	global_store_dwordx4 v[248:249], v[148:151], off offset:256
	s_branch .Lrn2_nx_7
.Lrn2_fin_7:
	global_store_dwordx4 v[164:165], v[156:159], off nt
	global_store_dwordx4 v[164:165], v[152:155], off offset:64 nt
	global_store_dwordx4 v[164:165], v[148:151], off offset:512 nt
	global_store_dwordx4 v[164:165], v[116:119], off offset:576 nt
.Lrn2_nx_7:
.LBB0_1066:
	v_readlane_b32 s84, v254, 43
	v_readlane_b32 s46, v254, 51
	s_mov_b64 s[2:3], 0
	v_readlane_b32 s85, v254, 44
	v_readlane_b32 s47, v254, 52
	s_movk_i32 s43, 0x90
